# QKV and BQ projection epilogues: ssq partial loads software-pipelined across the four row groups (two groups prefetched during the K-loop)
# speedup vs baseline: 1.0033x; 1.0033x over previous
.LBB0_322:
	s_ashr_i32 s17, s16, 31
	s_lshl_b64 s[18:19], s[16:17], 19
	s_add_u32 s18, s60, s18
	s_addc_u32 s19, s61, s19
	s_and_b64 s[22:23], s[0:1], exec
	s_cselect_b32 s3, s19, s25
	s_cselect_b32 s17, s18, s24
	s_ashr_i32 s15, s14, 31
	s_lshl_b64 s[22:23], s[14:15], 19
	s_add_u32 s22, s40, s22
	s_addc_u32 s23, s41, s23
	s_and_b64 s[38:39], s[0:1], exec
	s_cselect_b32 s15, s23, s29
	s_cselect_b32 s27, s22, s28
	s_add_u32 s24, s24, 0x40080
	s_addc_u32 s25, s25, 0
	s_add_u32 s68, s28, 0x100
	v_mov_b32_e32 v0, 0
	s_addc_u32 s69, s29, 0
	s_mov_b32 s70, -2
	v_mov_b32_e32 v1, v0
	v_mov_b32_e32 v2, v0
	v_mov_b32_e32 v3, v0
	v_mov_b32_e32 v4, v0
	v_mov_b32_e32 v5, v0
	v_mov_b32_e32 v6, v0
	v_mov_b32_e32 v7, v0
	v_mov_b32_e32 v16, v0
	v_mov_b32_e32 v17, v0
	v_mov_b32_e32 v18, v0
	v_mov_b32_e32 v19, v0
	v_mov_b32_e32 v20, v0
	v_mov_b32_e32 v21, v0
	v_mov_b32_e32 v22, v0
	v_mov_b32_e32 v23, v0
	v_mov_b32_e32 v32, v0
	v_mov_b32_e32 v33, v0
	v_mov_b32_e32 v34, v0
	v_mov_b32_e32 v35, v0
	v_mov_b32_e32 v60, v0
	v_mov_b32_e32 v61, v0
	v_mov_b32_e32 v62, v0
	v_mov_b32_e32 v63, v0
	v_mov_b32_e32 v96, v0
	v_mov_b32_e32 v97, v0
	v_mov_b32_e32 v98, v0
	v_mov_b32_e32 v99, v0
	v_mov_b32_e32 v100, v0
	v_mov_b32_e32 v101, v0
	v_mov_b32_e32 v102, v0
	v_mov_b32_e32 v103, v0
	v_mov_b32_e32 v8, v0
	v_mov_b32_e32 v9, v0
	v_mov_b32_e32 v10, v0
	v_mov_b32_e32 v11, v0
	v_mov_b32_e32 v12, v0
	v_mov_b32_e32 v13, v0
	s_waitcnt lgkmcnt(0)
	v_mov_b32_e32 v14, v0
	v_mov_b32_e32 v15, v0
	v_mov_b32_e32 v24, v0
	v_mov_b32_e32 v25, v0
	v_mov_b32_e32 v26, v0
	v_mov_b32_e32 v27, v0
	v_mov_b32_e32 v28, v0
	v_mov_b32_e32 v29, v0
	v_mov_b32_e32 v30, v0
	v_mov_b32_e32 v31, v0
	v_mov_b32_e32 v72, v0
	v_mov_b32_e32 v73, v0
	v_mov_b32_e32 v74, v0
	v_mov_b32_e32 v75, v0
	v_mov_b32_e32 v76, v0
	v_mov_b32_e32 v77, v0
	v_mov_b32_e32 v78, v0
	v_mov_b32_e32 v79, v0
	v_mov_b32_e32 v104, v0
	v_mov_b32_e32 v105, v0
	v_mov_b32_e32 v106, v0
	v_mov_b32_e32 v107, v0
	v_mov_b32_e32 v108, v0
	v_mov_b32_e32 v109, v0
	v_mov_b32_e32 v110, v0
	v_mov_b32_e32 v111, v0
	v_mov_b32_e32 v112, v0
	v_mov_b32_e32 v113, v0
	v_mov_b32_e32 v114, v0
	v_mov_b32_e32 v115, v0
	v_mov_b32_e32 v116, v0
	v_mov_b32_e32 v117, v0
	v_mov_b32_e32 v118, v0
	v_mov_b32_e32 v119, v0
	v_mov_b32_e32 v128, v0
	v_mov_b32_e32 v129, v0
	v_mov_b32_e32 v130, v0
	v_mov_b32_e32 v131, v0
	v_mov_b32_e32 v132, v0
	v_mov_b32_e32 v133, v0
	v_mov_b32_e32 v134, v0
	v_mov_b32_e32 v135, v0
	v_mov_b32_e32 v144, v0
	v_mov_b32_e32 v145, v0
	v_mov_b32_e32 v146, v0
	v_mov_b32_e32 v147, v0
	v_mov_b32_e32 v148, v0
	v_mov_b32_e32 v149, v0
	v_mov_b32_e32 v150, v0
	v_mov_b32_e32 v151, v0
	v_mov_b32_e32 v52, v0
	v_mov_b32_e32 v53, v0
	v_mov_b32_e32 v54, v0
	v_mov_b32_e32 v55, v0
	v_mov_b32_e32 v56, v0
	v_mov_b32_e32 v57, v0
	v_mov_b32_e32 v58, v0
	v_mov_b32_e32 v59, v0
	v_mov_b32_e32 v120, v0
	v_mov_b32_e32 v121, v0
	v_mov_b32_e32 v122, v0
	v_mov_b32_e32 v123, v0
	v_mov_b32_e32 v124, v0
	v_mov_b32_e32 v125, v0
	v_mov_b32_e32 v126, v0
	v_mov_b32_e32 v127, v0
	v_mov_b32_e32 v136, v0
	v_mov_b32_e32 v137, v0
	v_mov_b32_e32 v138, v0
	v_mov_b32_e32 v139, v0
	v_mov_b32_e32 v140, v0
	v_mov_b32_e32 v141, v0
	v_mov_b32_e32 v142, v0
	v_mov_b32_e32 v143, v0
	v_mov_b32_e32 v152, v0
	v_mov_b32_e32 v153, v0
	v_mov_b32_e32 v154, v0
	v_mov_b32_e32 v155, v0
	v_mov_b32_e32 v156, v0
	v_mov_b32_e32 v157, v0
	v_mov_b32_e32 v158, v0
	v_mov_b32_e32 v159, v0
	v_mov_b32_e32 v64, v0
	v_mov_b32_e32 v65, v0
	v_mov_b32_e32 v66, v0
	v_mov_b32_e32 v67, v0
	v_mov_b32_e32 v68, v0
	v_mov_b32_e32 v69, v0
	v_mov_b32_e32 v70, v0
	v_mov_b32_e32 v71, v0
	s_lshl_b32 s97, s2, 8
	s_add_i32 s97, s97, s50
	v_or_b32_e32 v254, s97, v192
	v_mov_b32_e32 v255, 0
	v_lshlrev_b64 v[254:255], 6, v[254:255]
	v_lshl_add_u64 v[254:255], v[170:171], 0, v[254:255]
	global_load_dwordx4 v[238:241], v[254:255], off
	global_load_dwordx4 v[242:245], v[254:255], off offset:1024
	global_load_dwordx4 v[246:249], v[254:255], off offset:2048
	global_load_dwordx4 v[250:253], v[254:255], off offset:3072

.LBB0_326:
	s_ashr_i32 s17, s26, 2
	s_cmp_lt_u32 s17, 2
	s_cselect_b64 s[24:25], -1, 0
	s_lshl_b32 s15, s2, 8
	s_add_i32 s15, s15, s50
	v_or_b32_e32 v180, s15, v192
	v_ashrrev_i32_e32 v181, 31, v180
	v_or_b32_e32 v182, 16, v180
	v_lshlrev_b64 v[36:37], 6, v[180:181]
	v_ashrrev_i32_e32 v183, 31, v182
	v_lshl_add_u64 v[36:37], v[170:171], 0, v[36:37]
	v_lshlrev_b64 v[40:41], 6, v[182:183]
	v_mov_b32_e32 v36, v238
	v_mov_b32_e32 v37, v239
	v_mov_b32_e32 v38, v240
	v_mov_b32_e32 v39, v241
	v_lshl_add_u64 v[40:41], v[170:171], 0, v[40:41]
	v_mov_b32_e32 v40, v242
	v_mov_b32_e32 v41, v243
	v_mov_b32_e32 v42, v244
	v_mov_b32_e32 v43, v245
	v_add_u32_e32 v254, 0x80, v180
	v_mov_b32_e32 v255, 0
	v_lshlrev_b64 v[254:255], 6, v[254:255]
	v_lshl_add_u64 v[254:255], v[170:171], 0, v[254:255]
	global_load_dwordx4 v[238:241], v[254:255], off
	global_load_dwordx4 v[242:245], v[254:255], off offset:1024
	v_and_b32_e32 v45, 64, v200
	v_xor_b32_e32 v44, 16, v200
	v_add_u32_e32 v45, 64, v45
	v_cmp_lt_i32_e32 vcc, v44, v45
	v_xor_b32_e32 v46, 32, v200
	s_and_b32 s2, s15, 0xfc0
	v_cndmask_b32_e32 v44, v200, v44, vcc
	v_lshlrev_b32_e32 v203, 2, v44
	v_cmp_lt_i32_e32 vcc, v46, v45
	s_and_b64 s[24:25], s[12:13], s[24:25]
	v_add_f32_e32 v36, v36, v37
	v_add_f32_e32 v37, v38, v39
	v_add_f32_e32 v36, v36, v37
	v_add_f32_e32 v37, v40, v41
	v_add_f32_e32 v38, v42, v43
	v_add_f32_e32 v37, v37, v38
	ds_bpermute_b32 v39, v203, v36
	ds_bpermute_b32 v38, v203, v37
	v_cndmask_b32_e32 v45, v200, v46, vcc
	v_lshlrev_b32_e32 v205, 2, v45
	v_or_b32_e32 v40, s2, v192
	s_waitcnt lgkmcnt(1)
	v_add_f32_e32 v168, v36, v39
	s_waitcnt lgkmcnt(0)
	v_add_f32_e32 v207, v37, v38
	ds_bpermute_b32 v184, v205, v168
	ds_bpermute_b32 v208, v205, v207
	v_cndmask_b32_e64 v36, 0, 1, s[24:25]
	v_cmp_ne_u32_e64 s[2:3], 1, v36
	s_andn2_b64 vcc, exec, s[24:25]
	v_lshlrev_b32_e32 v206, 6, v40
	s_cbranch_vccnz .LBB0_328
	global_load_dwordx4 v[80:83], v206, s[20:21] offset:48
	global_load_dwordx4 v[84:87], v206, s[20:21] offset:32
	global_load_dwordx4 v[88:91], v206, s[20:21] offset:16
	global_load_dwordx4 v[92:95], v206, s[20:21]
	global_load_dwordx4 v[36:39], v206, s[20:21] offset:1072
	global_load_dwordx4 v[40:43], v206, s[20:21] offset:1056
	global_load_dwordx4 v[44:47], v206, s[20:21] offset:1040
	global_load_dwordx4 v[48:51], v206, s[20:21] offset:1024

.LBB0_394:
	s_waitcnt lgkmcnt(3)
	v_cvt_pk_bf16_f32 v144, v156, v157
	s_waitcnt lgkmcnt(2)
	v_cvt_pk_bf16_f32 v145, v154, v155
	v_cvt_pk_bf16_f32 v146, v150, v151
	v_cvt_pk_bf16_f32 v147, v148, v149
	v_or_b32_e32 v148, 32, v180
	v_ashrrev_i32_e32 v149, 31, v148
	global_store_dwordx4 v[152:153], v[144:147], off offset:256
	s_and_b64 vcc, exec, s[2:3]
	s_nop 0
	v_lshlrev_b64 v[144:145], 6, v[148:149]
	v_lshl_add_u64 v[144:145], v[170:171], 0, v[144:145]
	v_mov_b32_e32 v150, v246
	v_mov_b32_e32 v151, v247
	v_mov_b32_e32 v152, v248
	v_mov_b32_e32 v153, v249
	global_load_dwordx4 v[246:249], v[254:255], off offset:2048
	v_or_b32_e32 v144, 48, v180
	v_ashrrev_i32_e32 v145, 31, v144
	v_lshlrev_b64 v[146:147], 6, v[144:145]
	v_lshl_add_u64 v[146:147], v[170:171], 0, v[146:147]
	v_mov_b32_e32 v154, v250
	v_mov_b32_e32 v155, v251
	v_mov_b32_e32 v156, v252
	v_mov_b32_e32 v157, v253
	global_load_dwordx4 v[250:253], v[254:255], off offset:3072
	v_add_f32_e32 v146, v150, v151
	v_add_f32_e32 v147, v152, v153
	v_add_f32_e32 v146, v146, v147
	v_add_f32_e32 v150, v154, v155
	v_add_f32_e32 v151, v156, v157
	v_add_f32_e32 v147, v150, v151
	ds_bpermute_b32 v150, v203, v146
	ds_bpermute_b32 v151, v203, v147
	s_waitcnt lgkmcnt(1)
	v_add_f32_e32 v146, v146, v150
	s_waitcnt lgkmcnt(0)
	v_add_f32_e32 v156, v147, v151
	ds_bpermute_b32 v147, v205, v146
	ds_bpermute_b32 v157, v205, v156
	s_cbranch_vccnz .LBB0_396
	global_load_dwordx4 v[80:83], v206, s[20:21] offset:2096
	global_load_dwordx4 v[84:87], v206, s[20:21] offset:2080
	global_load_dwordx4 v[88:91], v206, s[20:21] offset:2064
	global_load_dwordx4 v[92:95], v206, s[20:21] offset:2048
	global_load_dwordx4 v[36:39], v206, s[20:21] offset:3120
	global_load_dwordx4 v[40:43], v206, s[20:21] offset:3104
	global_load_dwordx4 v[44:47], v206, s[20:21] offset:3088
	global_load_dwordx4 v[48:51], v206, s[20:21] offset:3072

.LBB0_464:
	s_waitcnt lgkmcnt(3)
	v_cvt_pk_bf16_f32 v112, v124, v125
	s_addk_i32 s15, 0x80
	s_waitcnt lgkmcnt(2)
	v_cvt_pk_bf16_f32 v113, v122, v123
	v_cvt_pk_bf16_f32 v114, v118, v119
	v_cvt_pk_bf16_f32 v115, v116, v117
	global_store_dwordx4 v[120:121], v[112:115], off offset:256
	s_and_b64 vcc, exec, s[2:3]
	s_nop 0
	v_or_b32_e32 v112, s15, v192
	v_ashrrev_i32_e32 v113, 31, v112
	v_lshlrev_b64 v[114:115], 6, v[112:113]
	v_lshl_add_u64 v[114:115], v[170:171], 0, v[114:115]
	s_waitcnt vmcnt(10)
	v_mov_b32_e32 v116, v238
	v_mov_b32_e32 v117, v239
	v_mov_b32_e32 v118, v240
	v_mov_b32_e32 v119, v241
	v_or_b32_e32 v114, 16, v112
	v_ashrrev_i32_e32 v115, 31, v114
	v_lshlrev_b64 v[120:121], 6, v[114:115]
	v_lshl_add_u64 v[120:121], v[170:171], 0, v[120:121]
	v_mov_b32_e32 v120, v242
	v_mov_b32_e32 v121, v243
	v_mov_b32_e32 v122, v244
	v_mov_b32_e32 v123, v245
	s_and_b32 s15, s15, 0xfc0
	v_add_f32_e32 v116, v116, v117
	v_add_f32_e32 v117, v118, v119
	v_add_f32_e32 v116, v116, v117
	ds_bpermute_b32 v119, v203, v116
	v_add_f32_e32 v117, v120, v121
	v_add_f32_e32 v118, v122, v123
	v_add_f32_e32 v118, v117, v118
	ds_bpermute_b32 v120, v203, v118
	s_waitcnt lgkmcnt(1)
	v_add_f32_e32 v116, v116, v119
	ds_bpermute_b32 v117, v205, v116
	s_waitcnt lgkmcnt(1)
	v_add_f32_e32 v125, v118, v120
	ds_bpermute_b32 v126, v205, v125
	v_or_b32_e32 v118, s15, v192
	v_lshlrev_b32_e32 v124, 6, v118
	s_cbranch_vccnz .LBB0_466
	global_load_dwordx4 v[80:83], v124, s[20:21] offset:48
	global_load_dwordx4 v[84:87], v124, s[20:21] offset:32
	global_load_dwordx4 v[88:91], v124, s[20:21] offset:16
	global_load_dwordx4 v[92:95], v124, s[20:21]
	global_load_dwordx4 v[36:39], v124, s[20:21] offset:1072
	global_load_dwordx4 v[40:43], v124, s[20:21] offset:1056
	global_load_dwordx4 v[44:47], v124, s[20:21] offset:1040
	global_load_dwordx4 v[48:51], v124, s[20:21] offset:1024

.LBB0_534:
	s_waitcnt lgkmcnt(3)
	v_cvt_pk_bf16_f32 v32, v76, v77
	s_waitcnt lgkmcnt(2)
	v_cvt_pk_bf16_f32 v33, v74, v75
	v_cvt_pk_bf16_f32 v34, v62, v63
	v_cvt_pk_bf16_f32 v35, v60, v61
	v_or_b32_e32 v60, 32, v112
	v_ashrrev_i32_e32 v61, 31, v60
	global_store_dwordx4 v[72:73], v[32:35], off offset:256
	s_and_b64 vcc, exec, s[2:3]
	s_nop 0
	v_lshlrev_b64 v[32:33], 6, v[60:61]
	v_lshl_add_u64 v[32:33], v[170:171], 0, v[32:33]
	s_waitcnt vmcnt(8)
	v_mov_b32_e32 v72, v246
	v_mov_b32_e32 v73, v247
	v_mov_b32_e32 v74, v248
	v_mov_b32_e32 v75, v249
	v_or_b32_e32 v32, 48, v112
	v_ashrrev_i32_e32 v33, 31, v32
	v_lshlrev_b64 v[34:35], 6, v[32:33]
	v_lshl_add_u64 v[34:35], v[170:171], 0, v[34:35]
	s_waitcnt lgkmcnt(0)
	v_mov_b32_e32 v76, v250
	v_mov_b32_e32 v77, v251
	v_mov_b32_e32 v78, v252
	v_mov_b32_e32 v79, v253
	v_add_f32_e32 v34, v72, v73
	v_add_f32_e32 v35, v74, v75
	v_add_f32_e32 v34, v34, v35
	v_add_f32_e32 v62, v76, v77
	v_add_f32_e32 v63, v78, v79
	v_add_f32_e32 v35, v62, v63
	ds_bpermute_b32 v62, v203, v34
	ds_bpermute_b32 v63, v203, v35
	s_waitcnt lgkmcnt(1)
	v_add_f32_e32 v34, v34, v62
	s_waitcnt lgkmcnt(0)
	v_add_f32_e32 v76, v35, v63
	ds_bpermute_b32 v35, v205, v34
	ds_bpermute_b32 v77, v205, v76
	s_cbranch_vccnz .LBB0_536
	global_load_dwordx4 v[80:83], v124, s[20:21] offset:2096
	global_load_dwordx4 v[84:87], v124, s[20:21] offset:2080
	global_load_dwordx4 v[88:91], v124, s[20:21] offset:2064
	global_load_dwordx4 v[92:95], v124, s[20:21] offset:2048
	global_load_dwordx4 v[36:39], v124, s[20:21] offset:3120
	global_load_dwordx4 v[40:43], v124, s[20:21] offset:3104
	global_load_dwordx4 v[44:47], v124, s[20:21] offset:3088
	global_load_dwordx4 v[48:51], v124, s[20:21] offset:3072

.LBB0_1533:
	s_ashr_i32 s19, s18, 31
	s_lshl_b64 s[22:23], s[18:19], 19
	s_add_u32 s22, s60, s22
	s_addc_u32 s23, s61, s23
	s_and_b64 s[24:25], s[0:1], exec
	s_cselect_b32 s3, s23, s5
	s_cselect_b32 s19, s22, s4
	s_ashr_i32 s17, s16, 31
	s_lshl_b64 s[24:25], s[16:17], 19
	s_add_u32 s24, s46, s24
	s_addc_u32 s25, s47, s25
	s_and_b64 s[44:45], s[0:1], exec
	s_cselect_b32 s17, s25, s29
	s_cselect_b32 s27, s24, s28
	s_add_u32 s4, s4, 0x40080
	s_addc_u32 s5, s5, 0
	s_add_u32 s73, s28, 0x100
	v_mov_b32_e32 v0, 0
	s_addc_u32 s74, s29, 0
	s_mov_b32 s75, -2
	v_mov_b32_e32 v1, v0
	v_mov_b32_e32 v2, v0
	v_mov_b32_e32 v3, v0
	v_mov_b32_e32 v4, v0
	v_mov_b32_e32 v5, v0
	v_mov_b32_e32 v6, v0
	v_mov_b32_e32 v7, v0
	v_mov_b32_e32 v16, v0
	v_mov_b32_e32 v17, v0
	v_mov_b32_e32 v18, v0
	v_mov_b32_e32 v19, v0
	v_mov_b32_e32 v20, v0
	v_mov_b32_e32 v21, v0
	v_mov_b32_e32 v22, v0
	v_mov_b32_e32 v23, v0
	v_mov_b32_e32 v32, v0
	v_mov_b32_e32 v33, v0
	v_mov_b32_e32 v34, v0
	v_mov_b32_e32 v35, v0
	v_mov_b32_e32 v60, v0
	v_mov_b32_e32 v61, v0
	v_mov_b32_e32 v62, v0
	v_mov_b32_e32 v63, v0
	v_mov_b32_e32 v96, v0
	v_mov_b32_e32 v97, v0
	v_mov_b32_e32 v98, v0
	v_mov_b32_e32 v99, v0
	v_mov_b32_e32 v100, v0
	v_mov_b32_e32 v101, v0
	v_mov_b32_e32 v102, v0
	v_mov_b32_e32 v103, v0
	v_mov_b32_e32 v8, v0
	v_mov_b32_e32 v9, v0
	v_mov_b32_e32 v10, v0
	v_mov_b32_e32 v11, v0
	v_mov_b32_e32 v12, v0
	v_mov_b32_e32 v13, v0
	s_waitcnt lgkmcnt(0)
	v_mov_b32_e32 v14, v0
	v_mov_b32_e32 v15, v0
	v_mov_b32_e32 v24, v0
	v_mov_b32_e32 v25, v0
	v_mov_b32_e32 v26, v0
	v_mov_b32_e32 v27, v0
	v_mov_b32_e32 v28, v0
	v_mov_b32_e32 v29, v0
	v_mov_b32_e32 v30, v0
	v_mov_b32_e32 v31, v0
	v_mov_b32_e32 v72, v0
	v_mov_b32_e32 v73, v0
	v_mov_b32_e32 v74, v0
	v_mov_b32_e32 v75, v0
	v_mov_b32_e32 v76, v0
	v_mov_b32_e32 v77, v0
	v_mov_b32_e32 v78, v0
	v_mov_b32_e32 v79, v0
	v_mov_b32_e32 v104, v0
	v_mov_b32_e32 v105, v0
	v_mov_b32_e32 v106, v0
	v_mov_b32_e32 v107, v0
	v_mov_b32_e32 v108, v0
	v_mov_b32_e32 v109, v0
	v_mov_b32_e32 v110, v0
	v_mov_b32_e32 v111, v0
	v_mov_b32_e32 v112, v0
	v_mov_b32_e32 v113, v0
	v_mov_b32_e32 v114, v0
	v_mov_b32_e32 v115, v0
	v_mov_b32_e32 v116, v0
	v_mov_b32_e32 v117, v0
	v_mov_b32_e32 v118, v0
	v_mov_b32_e32 v119, v0
	v_mov_b32_e32 v128, v0
	v_mov_b32_e32 v129, v0
	v_mov_b32_e32 v130, v0
	v_mov_b32_e32 v131, v0
	v_mov_b32_e32 v132, v0
	v_mov_b32_e32 v133, v0
	v_mov_b32_e32 v134, v0
	v_mov_b32_e32 v135, v0
	v_mov_b32_e32 v144, v0
	v_mov_b32_e32 v145, v0
	v_mov_b32_e32 v146, v0
	v_mov_b32_e32 v147, v0
	v_mov_b32_e32 v148, v0
	v_mov_b32_e32 v149, v0
	v_mov_b32_e32 v150, v0
	v_mov_b32_e32 v151, v0
	v_mov_b32_e32 v52, v0
	v_mov_b32_e32 v53, v0
	v_mov_b32_e32 v54, v0
	v_mov_b32_e32 v55, v0
	v_mov_b32_e32 v56, v0
	v_mov_b32_e32 v57, v0
	v_mov_b32_e32 v58, v0
	v_mov_b32_e32 v59, v0
	v_mov_b32_e32 v120, v0
	v_mov_b32_e32 v121, v0
	v_mov_b32_e32 v122, v0
	v_mov_b32_e32 v123, v0
	v_mov_b32_e32 v124, v0
	v_mov_b32_e32 v125, v0
	v_mov_b32_e32 v126, v0
	v_mov_b32_e32 v127, v0
	v_mov_b32_e32 v136, v0
	v_mov_b32_e32 v137, v0
	v_mov_b32_e32 v138, v0
	v_mov_b32_e32 v139, v0
	v_mov_b32_e32 v140, v0
	v_mov_b32_e32 v141, v0
	v_mov_b32_e32 v142, v0
	v_mov_b32_e32 v143, v0
	v_mov_b32_e32 v152, v0
	v_mov_b32_e32 v153, v0
	v_mov_b32_e32 v154, v0
	v_mov_b32_e32 v155, v0
	v_mov_b32_e32 v156, v0
	v_mov_b32_e32 v157, v0
	v_mov_b32_e32 v158, v0
	v_mov_b32_e32 v159, v0
	v_mov_b32_e32 v64, v0
	v_mov_b32_e32 v65, v0
	v_mov_b32_e32 v66, v0
	v_mov_b32_e32 v67, v0
	v_mov_b32_e32 v68, v0
	v_mov_b32_e32 v69, v0
	v_mov_b32_e32 v70, v0
	v_mov_b32_e32 v71, v0
	s_lshl_b32 s97, s2, 8
	s_add_i32 s97, s97, s66
	v_or_b32_e32 v254, s97, v192
	v_mov_b32_e32 v255, 0
	v_lshlrev_b64 v[254:255], 6, v[254:255]
	v_lshl_add_u64 v[254:255], v[170:171], 0, v[254:255]
	global_load_dwordx4 v[238:241], v[254:255], off
	global_load_dwordx4 v[242:245], v[254:255], off offset:1024
	global_load_dwordx4 v[246:249], v[254:255], off offset:2048
	global_load_dwordx4 v[250:253], v[254:255], off offset:3072

.LBB0_1537:
	s_cmp_lt_u32 s26, 4
	s_cselect_b64 s[4:5], -1, 0
	s_lshl_b32 s17, s2, 8
	s_add_i32 s17, s17, s66
	v_or_b32_e32 v180, s17, v192
	v_ashrrev_i32_e32 v181, 31, v180
	v_or_b32_e32 v182, 16, v180
	v_lshlrev_b64 v[36:37], 6, v[180:181]
	v_ashrrev_i32_e32 v183, 31, v182
	v_lshl_add_u64 v[36:37], v[170:171], 0, v[36:37]
	v_lshlrev_b64 v[40:41], 6, v[182:183]
	v_mov_b32_e32 v36, v238
	v_mov_b32_e32 v37, v239
	v_mov_b32_e32 v38, v240
	v_mov_b32_e32 v39, v241
	v_lshl_add_u64 v[40:41], v[170:171], 0, v[40:41]
	v_mov_b32_e32 v40, v242
	v_mov_b32_e32 v41, v243
	v_mov_b32_e32 v42, v244
	v_mov_b32_e32 v43, v245
	v_add_u32_e32 v254, 0x80, v180
	v_mov_b32_e32 v255, 0
	v_lshlrev_b64 v[254:255], 6, v[254:255]
	v_lshl_add_u64 v[254:255], v[170:171], 0, v[254:255]
	global_load_dwordx4 v[238:241], v[254:255], off
	global_load_dwordx4 v[242:245], v[254:255], off offset:1024
	v_and_b32_e32 v45, 64, v200
	v_xor_b32_e32 v44, 16, v200
	v_add_u32_e32 v45, 64, v45
	v_cmp_lt_i32_e32 vcc, v44, v45
	v_xor_b32_e32 v46, 32, v200
	s_and_b32 s2, s17, 0xfc0
	v_cndmask_b32_e32 v44, v200, v44, vcc
	v_lshlrev_b32_e32 v203, 2, v44
	v_cmp_lt_i32_e32 vcc, v46, v45
	s_and_b64 s[28:29], s[14:15], s[4:5]
	v_add_f32_e32 v36, v36, v37
	v_add_f32_e32 v37, v38, v39
	v_add_f32_e32 v36, v36, v37
	v_add_f32_e32 v37, v40, v41
	v_add_f32_e32 v38, v42, v43
	v_add_f32_e32 v37, v37, v38
	ds_bpermute_b32 v39, v203, v36
	ds_bpermute_b32 v38, v203, v37
	v_cndmask_b32_e32 v45, v200, v46, vcc
	v_lshlrev_b32_e32 v205, 2, v45
	v_or_b32_e32 v40, s2, v192
	s_waitcnt lgkmcnt(1)
	v_add_f32_e32 v168, v36, v39
	s_waitcnt lgkmcnt(0)
	v_add_f32_e32 v207, v37, v38
	ds_bpermute_b32 v184, v205, v168
	ds_bpermute_b32 v208, v205, v207
	v_cndmask_b32_e64 v36, 0, 1, s[28:29]
	v_cmp_ne_u32_e64 s[2:3], 1, v36
	s_andn2_b64 vcc, exec, s[28:29]
	v_lshlrev_b32_e32 v206, 6, v40
	s_cbranch_vccnz .LBB0_1539
	global_load_dwordx4 v[80:83], v206, s[20:21] offset:48
	global_load_dwordx4 v[84:87], v206, s[20:21] offset:32
	global_load_dwordx4 v[88:91], v206, s[20:21] offset:16
	global_load_dwordx4 v[92:95], v206, s[20:21]
	global_load_dwordx4 v[36:39], v206, s[20:21] offset:1072
	global_load_dwordx4 v[40:43], v206, s[20:21] offset:1056
	global_load_dwordx4 v[44:47], v206, s[20:21] offset:1040
	global_load_dwordx4 v[48:51], v206, s[20:21] offset:1024

.LBB0_1675:
	s_waitcnt lgkmcnt(3)
	v_cvt_pk_bf16_f32 v112, v124, v125
	s_addk_i32 s17, 0x80
	s_waitcnt lgkmcnt(2)
	v_cvt_pk_bf16_f32 v113, v122, v123
	v_cvt_pk_bf16_f32 v114, v118, v119
	v_cvt_pk_bf16_f32 v115, v116, v117
	global_store_dwordx4 v[120:121], v[112:115], off offset:256
	s_and_b32 s4, s17, 0xfc0
	s_and_b64 vcc, exec, s[2:3]
	v_or_b32_e32 v112, s17, v192
	v_ashrrev_i32_e32 v113, 31, v112
	v_lshlrev_b64 v[114:115], 6, v[112:113]
	v_lshl_add_u64 v[114:115], v[170:171], 0, v[114:115]
	s_waitcnt vmcnt(10)
	v_mov_b32_e32 v116, v238
	v_mov_b32_e32 v117, v239
	v_mov_b32_e32 v118, v240
	v_mov_b32_e32 v119, v241
	v_or_b32_e32 v114, 16, v112
	v_ashrrev_i32_e32 v115, 31, v114
	v_lshlrev_b64 v[120:121], 6, v[114:115]
	v_lshl_add_u64 v[120:121], v[170:171], 0, v[120:121]
	v_mov_b32_e32 v120, v242
	v_mov_b32_e32 v121, v243
	v_mov_b32_e32 v122, v244
	v_mov_b32_e32 v123, v245
	v_add_f32_e32 v116, v116, v117
	v_add_f32_e32 v117, v118, v119
	v_add_f32_e32 v116, v116, v117
	ds_bpermute_b32 v119, v203, v116
	v_add_f32_e32 v117, v120, v121
	v_add_f32_e32 v118, v122, v123
	v_add_f32_e32 v118, v117, v118
	ds_bpermute_b32 v120, v203, v118
	s_waitcnt lgkmcnt(1)
	v_add_f32_e32 v116, v116, v119
	ds_bpermute_b32 v117, v205, v116
	s_waitcnt lgkmcnt(1)
	v_add_f32_e32 v125, v118, v120
	ds_bpermute_b32 v126, v205, v125
	v_or_b32_e32 v118, s4, v192
	v_lshlrev_b32_e32 v124, 6, v118
	s_cbranch_vccnz .LBB0_1677
	global_load_dwordx4 v[80:83], v124, s[20:21] offset:48
	global_load_dwordx4 v[84:87], v124, s[20:21] offset:32
	global_load_dwordx4 v[88:91], v124, s[20:21] offset:16
	global_load_dwordx4 v[92:95], v124, s[20:21]
	global_load_dwordx4 v[36:39], v124, s[20:21] offset:1072
	global_load_dwordx4 v[40:43], v124, s[20:21] offset:1056
	global_load_dwordx4 v[44:47], v124, s[20:21] offset:1040
	global_load_dwordx4 v[48:51], v124, s[20:21] offset:1024
